# v73 + FFN1 phase: workgroups that have one unit fewer than the busiest ones start 0/7/14/21 us late (by wgid&3) so tile epilogues (store bursts) of different workgroups stop coinciding
# baseline (speedup 1.0000x reference)
.LBB0_29:
	s_sub_i32 s0, s94, 42
	s_cmp_gt_u32 s0, -11
	s_cselect_b64 s[2:3], -1, 0
	s_cmp_lt_u32 s0, -10
	s_cselect_b64 s[36:37], -1, 0
	s_and_b64 s[0:1], s[36:37], exec
	v_writelane_b32 v254, s2, 32
	s_movk_i32 s0, 0x140
	s_cselect_b32 s28, s0, 0x100
	v_writelane_b32 v254, s3, 33
	s_lshl_b32 s0, s4, 1
	v_writelane_b32 v254, s0, 34
	v_readlane_b32 s0, v252, 8
	s_cmp_lt_i32 s0, s28
	s_cselect_b64 s[0:1], -1, 0
	v_writelane_b32 v254, s0, 35
	v_readlane_b32 s6, v252, 13
	v_readlane_b32 s7, v252, 14
	v_writelane_b32 v254, s1, 36
	v_readlane_b32 s0, v252, 31
	v_readlane_b32 s1, v252, 32
	s_and_b64 s[0:1], s[36:37], s[0:1]
	v_writelane_b32 v254, s0, 37
	s_mov_b32 s29, s65
	s_nop 0
	v_writelane_b32 v254, s1, 38
	s_add_i32 s0, s4, 1
	s_ashr_i32 s1, s0, 31
	s_mul_i32 s3, s0, 0x1f00000
	s_mul_hi_i32 s2, s0, 0x1f00000
	s_add_u32 s12, s6, s3
	s_addc_u32 s13, s7, s2
	s_add_u32 s2, s12, 0x1980000
	s_addc_u32 s3, s13, 0
	v_writelane_b32 v254, s2, 39
	s_mul_i32 s10, s0, 0xb00000
	s_mul_hi_i32 s5, s0, 0xb00000
	v_writelane_b32 v254, s3, 40
	s_add_u32 s2, s12, 0xe80000
	s_addc_u32 s3, s13, 0
	v_writelane_b32 v254, s2, 41
	s_mul_hi_i32 s11, s0, 0x1600000
	s_nop 0
	v_writelane_b32 v254, s3, 42
	s_lshl_b64 s[2:3], s[0:1], 22
	s_add_u32 s6, s12, 0xc80000
	s_addc_u32 s7, s13, 0
	v_writelane_b32 v254, s6, 43
	s_nop 1
	v_writelane_b32 v254, s7, 44
	s_lshl_b64 s[6:7], s[0:1], 20
	s_add_u32 s8, s12, 0xa80600
	s_addc_u32 s9, s13, 0
	v_writelane_b32 v254, s8, 45
	s_nop 1
	v_writelane_b32 v254, s9, 46
	s_lshl_b64 s[8:9], s[0:1], 21
	s_add_u32 s14, s12, 0xa80200
	v_writelane_b32 v254, s12, 47
	s_addc_u32 s15, s13, 0
	s_mul_i32 s1, s0, 0x1600000
	v_writelane_b32 v254, s13, 48
	v_writelane_b32 v254, s14, 49
	s_add_u32 s12, s88, s10
	s_addc_u32 s13, s89, s5
	v_writelane_b32 v254, s15, 50
	v_writelane_b32 v254, s12, 51
	s_nop 1
	v_writelane_b32 v254, s13, 52
	v_readlane_b32 s12, v252, 0
	v_readlane_b32 s18, v252, 6
	v_readlane_b32 s19, v252, 7
	s_add_u32 s10, s18, s1
	v_readlane_b32 s14, v252, 2
	s_addc_u32 s11, s19, s11
	v_readlane_b32 s15, v252, 3
	v_writelane_b32 v254, s10, 53
	s_add_u32 s2, s14, s2
	s_addc_u32 s3, s15, s3
	v_writelane_b32 v254, s11, 54
	v_writelane_b32 v254, s2, 55
	v_readlane_b32 s13, v252, 1
	s_mul_hi_i32 s1, s0, 0x1500000
	v_writelane_b32 v254, s3, 56
	s_add_u32 s2, s12, s6
	s_addc_u32 s3, s13, s7
	v_writelane_b32 v254, s2, 57
	s_mul_i32 s0, s0, 0x1500000
	v_readlane_b32 s16, v252, 4
	v_writelane_b32 v254, s3, 58
	s_add_u32 s2, s86, s8
	s_addc_u32 s3, s87, s9
	v_writelane_b32 v254, s2, 59
	s_add_u32 s0, s70, s0
	s_addc_u32 s1, s71, s1
	v_writelane_b32 v254, s3, 60
	v_writelane_b32 v254, s0, 61
	s_lshl_b32 s2, s4, 6
	s_cmp_lt_i32 s94, 12
	v_writelane_b32 v254, s1, 62
	v_writelane_b32 v254, s28, 63
	s_mul_hi_i32 s0, s4, 0x1f00000
	s_mul_i32 s1, s4, 0x1f00000
	v_writelane_b32 v255, s29, 0
	s_cselect_b64 s[4:5], -1, 0
	v_writelane_b32 v255, s4, 1
	s_cmp_lt_i32 s94, 22
	v_readlane_b32 s17, v252, 5
	v_writelane_b32 v255, s5, 2
	s_cselect_b64 s[4:5], -1, 0
	v_writelane_b32 v255, s4, 3
	s_cmp_lt_i32 s94, 32
	s_nop 0
	v_writelane_b32 v255, s5, 4
	s_cselect_b64 s[4:5], -1, 0
	v_writelane_b32 v255, s4, 5
	s_ashr_i32 s3, s2, 31
	s_nop 0
	v_writelane_b32 v255, s5, 6
	v_writelane_b32 v255, s2, 7
	s_nop 1
	v_writelane_b32 v255, s3, 8
	v_readlane_b32 s2, v254, 28
	v_readlane_b32 s3, v254, 29
	s_add_u32 s1, s2, s1
	s_addc_u32 s0, s3, s0
	s_add_u32 s1, s1, 0xa00000
	v_writelane_b32 v255, s1, 9
	s_addc_u32 s0, s0, 0
	v_writelane_b32 v255, s0, 10
	s_add_u32 s0, s2, 0xb200000
	s_addc_u32 s1, s3, 0
	v_writelane_b32 v255, s0, 11
	s_mov_b64 s[2:3], 0
	s_nop 0
	v_writelane_b32 v255, s1, 12
	v_readlane_b32 s0, v254, 21
	v_writelane_b32 v255, s2, 13
	s_cmp_lt_i32 s0, 4
	s_mov_b64 s[0:1], -1
	v_writelane_b32 v255, s3, 14
	s_cbranch_scc1 .LBB0_377
	s_and_b64 s[0:1], s[36:37], exec
	s_movk_i32 s0, 0x4800
	s_cselect_b32 s0, s0, 0x4000
	v_writelane_b32 v255, s0, 15
	v_readlane_b32 s0, v254, 21
	v_writelane_b32 v255, s36, 16
	s_cmp_gt_i32 s0, 5
	s_nop 0
	v_writelane_b32 v255, s37, 17
	s_cbranch_scc0 .LBB0_55
	s_cmp_gt_i32 s0, 7
	s_cbranch_scc0 .LBB0_56
	s_cmp_eq_u32 s0, 8
	s_mov_b64 s[0:1], -1
	s_cbranch_scc0 .LBB0_59
	v_readlane_b32 s0, v255, 15
	s_lshr_b32 s5, s0, 8
	v_mul_u32_u24_e64 v0, s5, 22
	v_readlane_b32 s0, v252, 8
	v_mov_b32_e32 v14, v236
	v_readfirstlane_b32 s2, v0
	v_cmp_ge_i32_e32 vcc, s0, v0
	s_nop 0
	v_readfirstlane_b32 s6, v14
	s_cbranch_vccnz .LBB0_58
	s_and_b32 s100, s2, 0xff
	s_cmp_eq_u32 s100, 0
	s_cbranch_scc1 .Lffn1_nodelay
	s_cmp_lt_u32 s0, s100
	s_cbranch_scc1 .Lffn1_nodelay
	s_and_b32 s100, s0, 3
	s_cmp_eq_u32 s100, 0
	s_cbranch_scc1 .Lffn1_nodelay
.Lffn1_dloop:
	s_sleep 127
	s_sleep 127
	s_sub_u32 s100, s100, 1
	s_cmp_lg_u32 s100, 0
	s_cbranch_scc1 .Lffn1_dloop
.Lffn1_nodelay:
	v_lshlrev_b32_e32 v0, 4, v14
	v_add_u32_e32 v1, 0x2000, v0
	v_ashrrev_i32_e32 v2, 31, v1
	v_lshrrev_b32_e32 v2, 22, v2
	v_add_u32_e32 v2, v1, v2
	v_ashrrev_i32_e32 v8, 10, v2
	v_mul_i32_i24_e32 v2, 0x400, v8
	v_sub_u32_e32 v1, v1, v2
	v_lshrrev_b32_e32 v2, 4, v1
	v_bitop3_b32 v1, v2, v1, 32 bitop3:0x6c
	v_ashrrev_i32_e32 v2, 31, v1
	v_readlane_b32 s0, v254, 28
	v_lshrrev_b32_e32 v2, 26, v2
	v_readlane_b32 s1, v254, 29
	s_add_u32 s13, s0, 0x16f00000
	v_add_u32_e32 v2, v1, v2
	v_lshlrev_b32_e32 v3, 3, v8
	s_addc_u32 s14, s1, 0
	v_readlane_b32 s0, v255, 9
	v_ashrrev_i32_e32 v9, 6, v2
	v_and_b32_e32 v3, -16, v3
	s_add_u32 s15, s0, 0xe80000
	v_readlane_b32 s0, v255, 10
	v_add_u32_e32 v3, v9, v3
	s_addc_u32 s16, s0, 0
	v_and_b32_e32 v4, 3, v9
	s_mov_b32 s0, 0x1fffe0
	v_lshrrev_b32_e32 v5, 2, v3
	v_lshlrev_b32_e32 v6, 1, v3
	v_and_b32_e32 v2, 0xc0, v2
	v_and_or_b32 v4, v3, s0, v4
	v_and_b32_e32 v5, 4, v5
	v_and_b32_e32 v6, 24, v6
	v_sub_u32_e32 v1, v1, v2
	v_or3_b32 v4, v4, v5, v6
	v_lshlrev_b32_e32 v5, 5, v8
	v_ashrrev_i16_sdwa v1, v239, sext(v1) dst_sel:DWORD dst_unused:UNUSED_PAD src0_sel:DWORD src1_sel:BYTE_0
	v_and_b32_e32 v5, 32, v5
	v_bfe_i32 v10, v1, 0, 16
	v_add_lshl_u32 v1, v5, v10, 1
	s_waitcnt vmcnt(0)
	v_lshl_add_u32 v194, v4, 11, v1
	v_lshl_add_u32 v196, v3, 11, v1
	v_bfe_i32 v1, v14, 27, 1
	v_lshrrev_b32_e32 v1, 22, v1
	v_add_u32_e32 v1, v0, v1
	v_and_b32_e32 v1, 0xfffffc00, v1
	v_sub_u32_e32 v0, v0, v1
	v_lshrrev_b32_e32 v1, 4, v0
	v_bitop3_b32 v1, v1, v0, 32 bitop3:0x6c
	v_ashrrev_i32_e32 v0, 31, v0
	v_lshrrev_b32_e32 v0, 26, v0
	v_add_u32_e32 v0, v1, v0
	v_ashrrev_i32_e32 v11, 6, v0
	v_ashrrev_i32_e32 v0, 31, v14
	v_lshrrev_b32_e32 v0, 26, v0
	v_add_u32_e32 v0, v14, v0
	v_ashrrev_i32_e32 v12, 6, v0
	v_lshlrev_b32_e32 v0, 3, v12
	v_and_b32_e32 v0, -16, v0
	v_add_u32_e32 v0, v11, v0
	v_and_b32_e32 v2, 3, v11
	s_lshr_b32 s1, s2, 3
	v_and_or_b32 v2, v0, s0, v2
	v_readlane_b32 s0, v253, 52
	v_writelane_b32 v255, s1, 32
	s_or_b32 s0, s1, s0
	v_readlane_b32 s1, v253, 54
	s_mul_i32 s0, s0, s1
	v_readlane_b32 s1, v253, 55
	s_add_i32 s0, s0, s1
	s_mul_hi_i32 s1, s0, 0x2e8ba2e9
	s_lshr_b32 s4, s1, 31
	s_ashr_i32 s1, s1, 5
	v_lshrrev_b32_e32 v3, 2, v0
	v_lshlrev_b32_e32 v4, 1, v0
	s_add_i32 s1, s1, s4
	v_and_b32_e32 v3, 4, v3
	v_and_b32_e32 v4, 24, v4
	s_lshl_b32 s4, s1, 3
	v_or3_b32 v2, v2, v3, v4
	v_mul_i32_i24_e32 v4, 64, v11
	v_writelane_b32 v255, s5, 18
	s_sub_i32 s5, s5, s4
	v_sub_u32_e32 v1, v1, v4
	s_min_i32 s5, s5, 8
	v_ashrrev_i16_sdwa v1, v239, sext(v1) dst_sel:DWORD dst_unused:UNUSED_PAD src0_sel:DWORD src1_sel:BYTE_0
	s_abs_i32 s8, s5
	v_bfe_i32 v13, v1, 0, 16
	v_cvt_f32_u32_e32 v1, s8
	v_lshlrev_b32_e32 v3, 5, v12
	v_and_b32_e32 v3, 32, v3
	v_add_lshl_u32 v3, v3, v13, 1
	v_lshl_add_u32 v200, v0, 11, v3
	v_rcp_iflag_f32_e32 v0, v1
	s_sub_i32 s10, 0, s8
	s_mulk_i32 s1, 0xb0
	s_sub_i32 s0, s0, s1
	v_mul_f32_e32 v0, 0x4f7ffffe, v0
	v_cvt_u32_f32_e32 v0, v0
	s_abs_i32 s9, s0
	s_ashr_i32 s3, s6, 6
	s_xor_b32 s1, s0, s5
	v_readfirstlane_b32 s11, v0
	s_mul_i32 s10, s10, s11
	s_mul_hi_u32 s10, s11, s10
	s_add_i32 s11, s11, s10
	s_mul_hi_u32 s10, s9, s11
	s_mul_i32 s11, s10, s8
	s_sub_i32 s9, s9, s11
	s_ashr_i32 s7, s6, 8
	s_lshl_b32 s53, s3, 10
	s_ashr_i32 s1, s1, 31
	s_add_i32 s11, s10, 1
	s_sub_i32 s12, s9, s8
	s_cmp_ge_u32 s9, s8
	s_cselect_b32 s10, s11, s10
	s_cselect_b32 s9, s12, s9
	s_add_i32 s11, s10, 1
	s_cmp_ge_u32 s9, s8
	s_cselect_b32 s8, s11, s10
	s_xor_b32 s8, s8, s1
	s_sub_i32 s44, s8, s1
	s_mul_i32 s1, s44, s5
	s_sub_i32 s0, s0, s1
	s_add_i32 s4, s4, s0
	s_lshl_b32 s42, s4, 1
	s_ashr_i32 s43, s42, 31
	s_ashr_i32 s45, s44, 31
	s_lshl_b64 s[4:5], s[42:43], 18
	s_lshl_b64 s[0:1], s[44:45], 19
	s_add_u32 s0, s15, s0
	s_addc_u32 s1, s16, s1
	s_add_i32 s43, s53, 16
	v_lshl_add_u32 v198, v2, 11, v3
	s_add_i32 m0, s43, 0x10000
	v_writelane_b32 v255, s15, 13
	global_load_lds_dwordx4 v198, s[0:1]
	s_add_i32 m0, s43, 0x12000
	s_add_u32 s8, s0, 0x40000
	global_load_lds_dwordx4 v194, s[0:1]
	s_addc_u32 s9, s1, 0
	s_add_i32 m0, s43, 0x14000
	v_writelane_b32 v255, s16, 26
	global_load_lds_dwordx4 v198, s[8:9]
	s_add_i32 m0, s43, 0x16000
	s_add_u32 s4, s13, s4
	s_addc_u32 s5, s14, s5
	s_add_i32 s45, s43, 0x2000
	global_load_lds_dwordx4 v194, s[8:9]
	v_writelane_b32 v255, s13, 22
	s_mov_b32 m0, s43
	s_add_u32 s8, s4, 0x40000
	v_writelane_b32 v255, s14, 24
	global_load_lds_dwordx4 v200, s[4:5]
	s_mov_b32 m0, s45
	s_addc_u32 s9, s5, 0
	s_add_i32 s14, s43, 0x4000
	global_load_lds_dwordx4 v196, s[4:5]
	s_mov_b32 m0, s14
	s_add_i32 s16, s43, 0x6000
	global_load_lds_dwordx4 v200, s[8:9]
	s_mov_b32 m0, s16
	s_cmp_eq_u32 s7, 1
	global_load_lds_dwordx4 v196, s[8:9]
	s_cselect_b64 s[8:9], -1, 0
	v_mov_b32_e32 v199, v161
	v_mov_b32_e32 v195, v161
	v_mov_b32_e32 v201, v161
	v_mov_b32_e32 v197, v161
	v_writelane_b32 v255, s8, 30
	v_lshl_add_u64 v[4:5], s[0:1], 0, v[198:199]
	v_lshl_add_u64 v[2:3], s[0:1], 0, v[194:195]
	v_lshl_add_u64 v[0:1], s[4:5], 0, v[200:201]
	v_writelane_b32 v255, s9, 31
	s_cmp_lg_u32 s7, 1
	v_lshl_add_u64 v[6:7], s[4:5], 0, v[196:197]
	s_cbranch_scc1 .LBB0_36
	s_barrier
